# same gate-load de-serialization applied to the RESID (phase 11) epilogue too: 8 dwordx2 gate loads up front, products in place after vmcnt(16)
# baseline (speedup 1.0000x reference)
.LBB0_650:
	s_ashr_i32 s0, s64, 5
	s_mul_hi_i32 s1, s0, 0x9000
	s_mul_i32 s0, s0, 0x9000
	v_lshl_or_b32 v130, s25, 8, v240
	s_add_u32 s0, s20, s0
	s_addc_u32 s1, s21, s1
	v_ashrrev_i32_e32 v131, 31, v130
	v_lshl_add_u64 v[132:133], v[130:131], 2, s[0:1]
	global_load_dwordx2 v[206:207], v[132:133], off offset:16
	global_load_dwordx2 v[204:205], v[132:133], off offset:24
	global_load_dwordx2 v[216:217], v[132:133], off
	global_load_dwordx2 v[212:213], v[132:133], off offset:8
	global_load_dwordx2 v[202:203], v[132:133], off offset:528
	global_load_dwordx2 v[200:201], v[132:133], off offset:536
	global_load_dwordx2 v[210:211], v[132:133], off offset:512
	global_load_dwordx2 v[208:209], v[132:133], off offset:520
	s_mov_b32 s25, s24
	v_lshlrev_b64 v[214:215], 1, v[130:131]
	s_and_b64 vcc, exec, s[4:5]
	v_lshl_add_u32 v122, s64, 8, v238
	v_readlane_b32 s0, v255, 19
	v_readlane_b32 s1, v255, 20
	v_ashrrev_i32_e32 v123, 31, v122
	v_lshl_add_u64 v[124:125], s[0:1], 0, v[214:215]
	v_lshlrev_b64 v[236:237], 11, v[122:123]
	v_lshl_add_u64 v[126:127], v[124:125], 0, v[236:237]
	global_load_dwordx4 v[250:253], v[126:127], off
	global_load_dwordx4 v[186:189], v[126:127], off offset:256
	v_or_b32_e32 v126, 16, v122
	v_ashrrev_i32_e32 v127, 31, v126
	v_lshlrev_b64 v[234:235], 11, v[126:127]
	v_lshl_add_u64 v[126:127], v[124:125], 0, v[234:235]
	global_load_dwordx4 v[182:185], v[126:127], off
	global_load_dwordx4 v[178:181], v[126:127], off offset:256
	v_or_b32_e32 v126, 32, v122
	v_ashrrev_i32_e32 v127, 31, v126
	v_lshlrev_b64 v[232:233], 11, v[126:127]
	v_lshl_add_u64 v[126:127], v[124:125], 0, v[232:233]
	global_load_dwordx4 v[174:177], v[126:127], off
	global_load_dwordx4 v[170:173], v[126:127], off offset:256
	v_or_b32_e32 v122, 48, v122
	v_ashrrev_i32_e32 v123, 31, v122
	v_lshlrev_b64 v[230:231], 11, v[122:123]
	v_lshl_add_u64 v[122:123], v[124:125], 0, v[230:231]
	global_load_dwordx4 v[166:169], v[122:123], off
	global_load_dwordx4 v[162:165], v[122:123], off offset:256
	v_lshl_add_u64 v[228:229], v[236:237], 0, s[58:59]
	s_mov_b64 s[0:1], 0x48000
	v_lshl_add_u64 v[122:123], v[124:125], 0, v[228:229]
	v_lshl_add_u64 v[226:227], v[236:237], 0, s[0:1]
	s_mov_b64 s[0:1], 0x50000
	global_load_dwordx4 v[158:161], v[122:123], off
	global_load_dwordx4 v[146:149], v[122:123], off offset:256
	v_lshl_add_u64 v[122:123], v[124:125], 0, v[226:227]
	v_lshl_add_u64 v[220:221], v[236:237], 0, s[0:1]
	s_mov_b64 s[0:1], 0x58000
	global_load_dwordx4 v[142:145], v[122:123], off
	global_load_dwordx4 v[138:141], v[122:123], off offset:256
	v_lshl_add_u64 v[122:123], v[124:125], 0, v[220:221]
	v_lshl_add_u64 v[218:219], v[236:237], 0, s[0:1]
	global_load_dwordx4 v[134:137], v[122:123], off
	global_load_dwordx4 v[130:133], v[122:123], off offset:256
	v_lshl_add_u64 v[122:123], v[124:125], 0, v[218:219]
	global_load_dwordx4 v[126:129], v[122:123], off
	s_nop 0
	global_load_dwordx4 v[122:125], v[122:123], off offset:256
	v_readlane_b32 s0, v255, 42
	v_readlane_b32 s1, v255, 43
	s_waitcnt vmcnt(16)
	v_pk_mul_f32 v[204:205], s[24:25], v[204:205]
	v_pk_mul_f32 v[212:213], s[24:25], v[212:213]
	v_pk_mul_f32 v[216:217], s[0:1], v[216:217]
	v_pk_mul_f32 v[206:207], s[0:1], v[206:207]
	v_pk_mul_f32 v[202:203], s[0:1], v[202:203]
	v_pk_mul_f32 v[210:211], s[0:1], v[210:211]
	v_pk_mul_f32 v[200:201], s[24:25], v[200:201]
	v_pk_mul_f32 v[208:209], s[24:25], v[208:209]
	s_mov_b64 s[0:1], -1
	s_waitcnt vmcnt(15)
	v_cvt_f32_f16_e32 v222, v250
	v_cvt_f32_f16_sdwa v223, v250 dst_sel:DWORD dst_unused:UNUSED_PAD src0_sel:WORD_1
	v_cvt_f32_f16_e32 v224, v251
	v_cvt_f32_f16_sdwa v225, v251 dst_sel:DWORD dst_unused:UNUSED_PAD src0_sel:WORD_1
	v_pk_fma_f32 v[154:155], v[154:155], v[216:217], v[222:223]
	v_cvt_f32_f16_e32 v222, v252
	v_pk_fma_f32 v[156:157], v[156:157], v[212:213], v[224:225]
	v_cvt_f32_f16_sdwa v223, v252 dst_sel:DWORD dst_unused:UNUSED_PAD src0_sel:WORD_1
	v_cvt_f32_f16_e32 v224, v253
	v_cvt_f32_f16_sdwa v225, v253 dst_sel:DWORD dst_unused:UNUSED_PAD src0_sel:WORD_1
	v_pk_fma_f32 v[224:225], v[152:153], v[204:205], v[224:225]
	v_pk_fma_f32 v[152:153], v[150:151], v[206:207], v[222:223]
	v_med3_f32 v150, v154, s95, v247
	v_med3_f32 v151, v155, s95, v247
	v_cvt_pk_f16_f32 v150, v150, v151
	v_med3_f32 v151, v156, s95, v247
	v_med3_f32 v154, v157, s95, v247
	v_med3_f32 v152, v152, s95, v247
	v_med3_f32 v153, v153, s95, v247
	v_cvt_pk_f16_f32 v151, v151, v154
	v_cvt_pk_f16_f32 v152, v152, v153
	v_med3_f32 v153, v224, s95, v247
	v_med3_f32 v154, v225, s95, v247
	v_cvt_pk_f16_f32 v153, v153, v154
	v_lshl_add_u64 v[154:155], s[26:27], 0, v[236:237]
	v_lshl_add_u64 v[154:155], v[154:155], 0, v[214:215]
	global_store_dwordx4 v[154:155], v[150:153], off
	s_waitcnt vmcnt(15)
	s_nop 0
	v_cvt_f32_f16_e32 v150, v186
	v_cvt_f32_f16_sdwa v151, v186 dst_sel:DWORD dst_unused:UNUSED_PAD src0_sel:WORD_1
	v_cvt_f32_f16_e32 v152, v187
	v_cvt_f32_f16_sdwa v153, v187 dst_sel:DWORD dst_unused:UNUSED_PAD src0_sel:WORD_1
	v_pk_fma_f32 v[118:119], v[118:119], v[210:211], v[150:151]
	v_cvt_f32_f16_e32 v150, v188
	v_pk_fma_f32 v[120:121], v[120:121], v[208:209], v[152:153]
	v_cvt_f32_f16_sdwa v151, v188 dst_sel:DWORD dst_unused:UNUSED_PAD src0_sel:WORD_1
	v_cvt_f32_f16_e32 v152, v189
	v_cvt_f32_f16_sdwa v153, v189 dst_sel:DWORD dst_unused:UNUSED_PAD src0_sel:WORD_1
	v_pk_fma_f32 v[152:153], v[112:113], v[200:201], v[152:153]
	v_pk_fma_f32 v[112:113], v[110:111], v[202:203], v[150:151]
	v_med3_f32 v110, v118, s95, v247
	v_med3_f32 v111, v119, s95, v247
	v_cvt_pk_f16_f32 v110, v110, v111
	v_med3_f32 v111, v120, s95, v247
	v_med3_f32 v118, v121, s95, v247
	v_med3_f32 v112, v112, s95, v247
	v_med3_f32 v113, v113, s95, v247
	v_cvt_pk_f16_f32 v111, v111, v118
	v_cvt_pk_f16_f32 v112, v112, v113
	v_med3_f32 v113, v152, s95, v247
	v_med3_f32 v118, v153, s95, v247
	v_cvt_pk_f16_f32 v113, v113, v118
	global_store_dwordx4 v[154:155], v[110:113], off offset:256
	s_waitcnt vmcnt(15)
	s_nop 0
	v_cvt_f32_f16_e32 v110, v182
	v_cvt_f32_f16_sdwa v111, v182 dst_sel:DWORD dst_unused:UNUSED_PAD src0_sel:WORD_1
	v_cvt_f32_f16_e32 v112, v183
	v_cvt_f32_f16_sdwa v113, v183 dst_sel:DWORD dst_unused:UNUSED_PAD src0_sel:WORD_1
	v_pk_fma_f32 v[110:111], v[114:115], v[216:217], v[110:111]
	v_cvt_f32_f16_e32 v114, v184
	v_pk_fma_f32 v[112:113], v[116:117], v[212:213], v[112:113]
	v_cvt_f32_f16_sdwa v115, v184 dst_sel:DWORD dst_unused:UNUSED_PAD src0_sel:WORD_1
	v_cvt_f32_f16_e32 v116, v185
	v_cvt_f32_f16_sdwa v117, v185 dst_sel:DWORD dst_unused:UNUSED_PAD src0_sel:WORD_1
	v_pk_fma_f32 v[116:117], v[108:109], v[204:205], v[116:117]
	v_pk_fma_f32 v[108:109], v[106:107], v[206:207], v[114:115]
	v_med3_f32 v106, v110, s95, v247
	v_med3_f32 v107, v111, s95, v247
	v_cvt_pk_f16_f32 v106, v106, v107
	v_med3_f32 v107, v112, s95, v247
	v_med3_f32 v110, v113, s95, v247
	v_med3_f32 v108, v108, s95, v247
	v_med3_f32 v109, v109, s95, v247
	v_cvt_pk_f16_f32 v107, v107, v110
	v_cvt_pk_f16_f32 v108, v108, v109
	v_med3_f32 v109, v116, s95, v247
	v_med3_f32 v110, v117, s95, v247
	v_cvt_pk_f16_f32 v109, v109, v110
	v_lshl_add_u64 v[110:111], s[26:27], 0, v[234:235]
	v_lshl_add_u64 v[110:111], v[110:111], 0, v[214:215]
	global_store_dwordx4 v[110:111], v[106:109], off
	s_waitcnt vmcnt(15)
	s_nop 0
	v_cvt_f32_f16_e32 v106, v178
	v_cvt_f32_f16_sdwa v107, v178 dst_sel:DWORD dst_unused:UNUSED_PAD src0_sel:WORD_1
	v_cvt_f32_f16_e32 v108, v179
	v_cvt_f32_f16_sdwa v109, v179 dst_sel:DWORD dst_unused:UNUSED_PAD src0_sel:WORD_1
	v_pk_fma_f32 v[102:103], v[102:103], v[210:211], v[106:107]
	v_cvt_f32_f16_e32 v106, v180
	v_pk_fma_f32 v[104:105], v[104:105], v[208:209], v[108:109]
	v_cvt_f32_f16_sdwa v107, v180 dst_sel:DWORD dst_unused:UNUSED_PAD src0_sel:WORD_1
	v_cvt_f32_f16_e32 v108, v181
	v_cvt_f32_f16_sdwa v109, v181 dst_sel:DWORD dst_unused:UNUSED_PAD src0_sel:WORD_1
	v_pk_fma_f32 v[108:109], v[96:97], v[200:201], v[108:109]
	v_pk_fma_f32 v[96:97], v[94:95], v[202:203], v[106:107]
	v_med3_f32 v94, v102, s95, v247
	v_med3_f32 v95, v103, s95, v247
	v_cvt_pk_f16_f32 v94, v94, v95
	v_med3_f32 v95, v104, s95, v247
	v_med3_f32 v102, v105, s95, v247
	v_med3_f32 v96, v96, s95, v247
	v_med3_f32 v97, v97, s95, v247
	v_cvt_pk_f16_f32 v95, v95, v102
	v_cvt_pk_f16_f32 v96, v96, v97
	v_med3_f32 v97, v108, s95, v247
	v_med3_f32 v102, v109, s95, v247
	v_cvt_pk_f16_f32 v97, v97, v102
	global_store_dwordx4 v[110:111], v[94:97], off offset:256
	s_waitcnt vmcnt(15)
	s_nop 0
	v_cvt_f32_f16_e32 v94, v174
	v_cvt_f32_f16_sdwa v95, v174 dst_sel:DWORD dst_unused:UNUSED_PAD src0_sel:WORD_1
	v_cvt_f32_f16_e32 v96, v175
	v_cvt_f32_f16_sdwa v97, v175 dst_sel:DWORD dst_unused:UNUSED_PAD src0_sel:WORD_1
	v_pk_fma_f32 v[94:95], v[98:99], v[216:217], v[94:95]
	v_cvt_f32_f16_e32 v98, v176
	v_pk_fma_f32 v[96:97], v[100:101], v[212:213], v[96:97]
	v_cvt_f32_f16_sdwa v99, v176 dst_sel:DWORD dst_unused:UNUSED_PAD src0_sel:WORD_1
	v_cvt_f32_f16_e32 v100, v177
	v_cvt_f32_f16_sdwa v101, v177 dst_sel:DWORD dst_unused:UNUSED_PAD src0_sel:WORD_1
	v_pk_fma_f32 v[100:101], v[92:93], v[204:205], v[100:101]
	v_pk_fma_f32 v[92:93], v[90:91], v[206:207], v[98:99]
	v_med3_f32 v90, v94, s95, v247
	v_med3_f32 v91, v95, s95, v247
	v_cvt_pk_f16_f32 v90, v90, v91
	v_med3_f32 v91, v96, s95, v247
	v_med3_f32 v94, v97, s95, v247
	v_med3_f32 v92, v92, s95, v247
	v_med3_f32 v93, v93, s95, v247
	v_cvt_pk_f16_f32 v91, v91, v94
	v_cvt_pk_f16_f32 v92, v92, v93
	v_med3_f32 v93, v100, s95, v247
	v_med3_f32 v94, v101, s95, v247
	v_cvt_pk_f16_f32 v93, v93, v94
	v_lshl_add_u64 v[94:95], s[26:27], 0, v[232:233]
	v_lshl_add_u64 v[94:95], v[94:95], 0, v[214:215]
	global_store_dwordx4 v[94:95], v[90:93], off
	s_waitcnt vmcnt(15)
	s_nop 0
	v_cvt_f32_f16_e32 v90, v170
	v_cvt_f32_f16_sdwa v91, v170 dst_sel:DWORD dst_unused:UNUSED_PAD src0_sel:WORD_1
	v_cvt_f32_f16_e32 v92, v171
	v_cvt_f32_f16_sdwa v93, v171 dst_sel:DWORD dst_unused:UNUSED_PAD src0_sel:WORD_1
	v_pk_fma_f32 v[86:87], v[86:87], v[210:211], v[90:91]
	v_cvt_f32_f16_e32 v90, v172
	v_pk_fma_f32 v[88:89], v[88:89], v[208:209], v[92:93]
	v_cvt_f32_f16_sdwa v91, v172 dst_sel:DWORD dst_unused:UNUSED_PAD src0_sel:WORD_1
	v_cvt_f32_f16_e32 v92, v173
	v_cvt_f32_f16_sdwa v93, v173 dst_sel:DWORD dst_unused:UNUSED_PAD src0_sel:WORD_1
	v_pk_fma_f32 v[92:93], v[80:81], v[200:201], v[92:93]
	v_pk_fma_f32 v[80:81], v[78:79], v[202:203], v[90:91]
	v_med3_f32 v78, v86, s95, v247
	v_med3_f32 v79, v87, s95, v247
	v_cvt_pk_f16_f32 v78, v78, v79
	v_med3_f32 v79, v88, s95, v247
	v_med3_f32 v86, v89, s95, v247
	v_med3_f32 v80, v80, s95, v247
	v_med3_f32 v81, v81, s95, v247
	v_cvt_pk_f16_f32 v79, v79, v86
	v_cvt_pk_f16_f32 v80, v80, v81
	v_med3_f32 v81, v92, s95, v247
	v_med3_f32 v86, v93, s95, v247
	v_cvt_pk_f16_f32 v81, v81, v86
	global_store_dwordx4 v[94:95], v[78:81], off offset:256
	s_waitcnt vmcnt(15)
	s_nop 0
	v_cvt_f32_f16_e32 v78, v166
	v_cvt_f32_f16_sdwa v79, v166 dst_sel:DWORD dst_unused:UNUSED_PAD src0_sel:WORD_1
	v_cvt_f32_f16_e32 v80, v167
	v_cvt_f32_f16_sdwa v81, v167 dst_sel:DWORD dst_unused:UNUSED_PAD src0_sel:WORD_1
	v_pk_fma_f32 v[78:79], v[82:83], v[216:217], v[78:79]
	v_cvt_f32_f16_e32 v82, v168
	v_pk_fma_f32 v[80:81], v[84:85], v[212:213], v[80:81]
	v_cvt_f32_f16_sdwa v83, v168 dst_sel:DWORD dst_unused:UNUSED_PAD src0_sel:WORD_1
	v_cvt_f32_f16_e32 v84, v169
	v_cvt_f32_f16_sdwa v85, v169 dst_sel:DWORD dst_unused:UNUSED_PAD src0_sel:WORD_1
	v_pk_fma_f32 v[84:85], v[76:77], v[204:205], v[84:85]
	v_pk_fma_f32 v[76:77], v[74:75], v[206:207], v[82:83]
	v_med3_f32 v74, v78, s95, v247
	v_med3_f32 v75, v79, s95, v247
	v_cvt_pk_f16_f32 v74, v74, v75
	v_med3_f32 v75, v80, s95, v247
	v_med3_f32 v78, v81, s95, v247
	v_med3_f32 v76, v76, s95, v247
	v_med3_f32 v77, v77, s95, v247
	v_cvt_pk_f16_f32 v75, v75, v78
	v_cvt_pk_f16_f32 v76, v76, v77
	v_med3_f32 v77, v84, s95, v247
	v_med3_f32 v78, v85, s95, v247
	v_cvt_pk_f16_f32 v77, v77, v78
	v_lshl_add_u64 v[78:79], s[26:27], 0, v[230:231]
	v_lshl_add_u64 v[78:79], v[78:79], 0, v[214:215]
	global_store_dwordx4 v[78:79], v[74:77], off
	s_waitcnt vmcnt(15)
	s_nop 0
	v_cvt_f32_f16_e32 v74, v162
	v_cvt_f32_f16_sdwa v75, v162 dst_sel:DWORD dst_unused:UNUSED_PAD src0_sel:WORD_1
	v_cvt_f32_f16_e32 v76, v163
	v_cvt_f32_f16_sdwa v77, v163 dst_sel:DWORD dst_unused:UNUSED_PAD src0_sel:WORD_1
	v_pk_fma_f32 v[70:71], v[70:71], v[210:211], v[74:75]
	v_cvt_f32_f16_e32 v74, v164
	v_pk_fma_f32 v[72:73], v[72:73], v[208:209], v[76:77]
	v_cvt_f32_f16_sdwa v75, v164 dst_sel:DWORD dst_unused:UNUSED_PAD src0_sel:WORD_1
	v_cvt_f32_f16_e32 v76, v165
	v_cvt_f32_f16_sdwa v77, v165 dst_sel:DWORD dst_unused:UNUSED_PAD src0_sel:WORD_1
	v_pk_fma_f32 v[76:77], v[68:69], v[200:201], v[76:77]
	v_pk_fma_f32 v[68:69], v[66:67], v[202:203], v[74:75]
	v_med3_f32 v66, v70, s95, v247
	v_med3_f32 v67, v71, s95, v247
	v_cvt_pk_f16_f32 v66, v66, v67
	v_med3_f32 v67, v72, s95, v247
	v_med3_f32 v70, v73, s95, v247
	v_med3_f32 v68, v68, s95, v247
	v_med3_f32 v69, v69, s95, v247
	v_cvt_pk_f16_f32 v67, v67, v70
	v_cvt_pk_f16_f32 v68, v68, v69
	v_med3_f32 v69, v76, s95, v247
	v_med3_f32 v70, v77, s95, v247
	v_cvt_pk_f16_f32 v69, v69, v70
	global_store_dwordx4 v[78:79], v[66:69], off offset:256
	s_waitcnt vmcnt(15)
	s_nop 0
	v_cvt_f32_f16_e32 v66, v158
	v_cvt_f32_f16_sdwa v67, v158 dst_sel:DWORD dst_unused:UNUSED_PAD src0_sel:WORD_1
	v_cvt_f32_f16_e32 v68, v159
	v_cvt_f32_f16_sdwa v69, v159 dst_sel:DWORD dst_unused:UNUSED_PAD src0_sel:WORD_1
	v_pk_fma_f32 v[62:63], v[62:63], v[216:217], v[66:67]
	v_cvt_f32_f16_e32 v66, v160
	v_pk_fma_f32 v[64:65], v[64:65], v[212:213], v[68:69]
	v_cvt_f32_f16_sdwa v67, v160 dst_sel:DWORD dst_unused:UNUSED_PAD src0_sel:WORD_1
	v_cvt_f32_f16_e32 v68, v161
	v_cvt_f32_f16_sdwa v69, v161 dst_sel:DWORD dst_unused:UNUSED_PAD src0_sel:WORD_1
	v_pk_fma_f32 v[68:69], v[60:61], v[204:205], v[68:69]
	v_pk_fma_f32 v[60:61], v[58:59], v[206:207], v[66:67]
	v_med3_f32 v58, v62, s95, v247
	v_med3_f32 v59, v63, s95, v247
	v_cvt_pk_f16_f32 v58, v58, v59
	v_med3_f32 v59, v64, s95, v247
	v_med3_f32 v62, v65, s95, v247
	v_med3_f32 v60, v60, s95, v247
	v_med3_f32 v61, v61, s95, v247
	v_cvt_pk_f16_f32 v59, v59, v62
	v_cvt_pk_f16_f32 v60, v60, v61
	v_med3_f32 v61, v68, s95, v247
	v_med3_f32 v62, v69, s95, v247
	v_cvt_pk_f16_f32 v61, v61, v62
	v_lshl_add_u64 v[62:63], s[26:27], 0, v[228:229]
	v_lshl_add_u64 v[62:63], v[62:63], 0, v[214:215]
	global_store_dwordx4 v[62:63], v[58:61], off
	s_waitcnt vmcnt(15)
	s_nop 0
	v_cvt_f32_f16_e32 v58, v146
	v_cvt_f32_f16_sdwa v59, v146 dst_sel:DWORD dst_unused:UNUSED_PAD src0_sel:WORD_1
	v_cvt_f32_f16_e32 v60, v147
	v_cvt_f32_f16_sdwa v61, v147 dst_sel:DWORD dst_unused:UNUSED_PAD src0_sel:WORD_1
	v_pk_fma_f32 v[54:55], v[54:55], v[210:211], v[58:59]
	v_cvt_f32_f16_e32 v58, v148
	v_pk_fma_f32 v[56:57], v[56:57], v[208:209], v[60:61]
	v_cvt_f32_f16_sdwa v59, v148 dst_sel:DWORD dst_unused:UNUSED_PAD src0_sel:WORD_1
	v_cvt_f32_f16_e32 v60, v149
	v_cvt_f32_f16_sdwa v61, v149 dst_sel:DWORD dst_unused:UNUSED_PAD src0_sel:WORD_1
	v_pk_fma_f32 v[60:61], v[48:49], v[200:201], v[60:61]
	v_pk_fma_f32 v[48:49], v[46:47], v[202:203], v[58:59]
	v_med3_f32 v46, v54, s95, v247
	v_med3_f32 v47, v55, s95, v247
	v_cvt_pk_f16_f32 v46, v46, v47
	v_med3_f32 v47, v56, s95, v247
	v_med3_f32 v54, v57, s95, v247
	v_med3_f32 v48, v48, s95, v247
	v_med3_f32 v49, v49, s95, v247
	v_cvt_pk_f16_f32 v47, v47, v54
	v_cvt_pk_f16_f32 v48, v48, v49
	v_med3_f32 v49, v60, s95, v247
	v_med3_f32 v54, v61, s95, v247
	v_cvt_pk_f16_f32 v49, v49, v54
	global_store_dwordx4 v[62:63], v[46:49], off offset:256
	s_waitcnt vmcnt(15)
	s_nop 0
	v_cvt_f32_f16_e32 v46, v142
	v_cvt_f32_f16_sdwa v47, v142 dst_sel:DWORD dst_unused:UNUSED_PAD src0_sel:WORD_1
	v_cvt_f32_f16_e32 v48, v143
	v_cvt_f32_f16_sdwa v49, v143 dst_sel:DWORD dst_unused:UNUSED_PAD src0_sel:WORD_1
	v_pk_fma_f32 v[46:47], v[50:51], v[216:217], v[46:47]
	v_cvt_f32_f16_e32 v50, v144
	v_pk_fma_f32 v[48:49], v[52:53], v[212:213], v[48:49]
	v_cvt_f32_f16_sdwa v51, v144 dst_sel:DWORD dst_unused:UNUSED_PAD src0_sel:WORD_1
	v_cvt_f32_f16_e32 v52, v145
	v_cvt_f32_f16_sdwa v53, v145 dst_sel:DWORD dst_unused:UNUSED_PAD src0_sel:WORD_1
	v_pk_fma_f32 v[52:53], v[44:45], v[204:205], v[52:53]
	v_pk_fma_f32 v[44:45], v[42:43], v[206:207], v[50:51]
	v_med3_f32 v42, v46, s95, v247
	v_med3_f32 v43, v47, s95, v247
	v_cvt_pk_f16_f32 v42, v42, v43
	v_med3_f32 v43, v48, s95, v247
	v_med3_f32 v46, v49, s95, v247
	v_med3_f32 v44, v44, s95, v247
	v_med3_f32 v45, v45, s95, v247
	v_cvt_pk_f16_f32 v43, v43, v46
	v_cvt_pk_f16_f32 v44, v44, v45
	v_med3_f32 v45, v52, s95, v247
	v_med3_f32 v46, v53, s95, v247
	v_cvt_pk_f16_f32 v45, v45, v46
	v_lshl_add_u64 v[46:47], s[26:27], 0, v[226:227]
	v_lshl_add_u64 v[46:47], v[46:47], 0, v[214:215]
	global_store_dwordx4 v[46:47], v[42:45], off
	s_waitcnt vmcnt(15)
	s_nop 0
	v_cvt_f32_f16_e32 v42, v138
	v_cvt_f32_f16_sdwa v43, v138 dst_sel:DWORD dst_unused:UNUSED_PAD src0_sel:WORD_1
	v_cvt_f32_f16_e32 v44, v139
	v_cvt_f32_f16_sdwa v45, v139 dst_sel:DWORD dst_unused:UNUSED_PAD src0_sel:WORD_1
	v_pk_fma_f32 v[38:39], v[38:39], v[210:211], v[42:43]
	v_cvt_f32_f16_e32 v42, v140
	v_pk_fma_f32 v[40:41], v[40:41], v[208:209], v[44:45]
	v_cvt_f32_f16_sdwa v43, v140 dst_sel:DWORD dst_unused:UNUSED_PAD src0_sel:WORD_1
	v_cvt_f32_f16_e32 v44, v141
	v_cvt_f32_f16_sdwa v45, v141 dst_sel:DWORD dst_unused:UNUSED_PAD src0_sel:WORD_1
	v_pk_fma_f32 v[44:45], v[32:33], v[200:201], v[44:45]
	v_pk_fma_f32 v[32:33], v[30:31], v[202:203], v[42:43]
	v_med3_f32 v30, v38, s95, v247
	v_med3_f32 v31, v39, s95, v247
	v_cvt_pk_f16_f32 v30, v30, v31
	v_med3_f32 v31, v40, s95, v247
	v_med3_f32 v38, v41, s95, v247
	v_med3_f32 v32, v32, s95, v247
	v_med3_f32 v33, v33, s95, v247
	v_cvt_pk_f16_f32 v31, v31, v38
	v_cvt_pk_f16_f32 v32, v32, v33
	v_med3_f32 v33, v44, s95, v247
	v_med3_f32 v38, v45, s95, v247
	v_cvt_pk_f16_f32 v33, v33, v38
	global_store_dwordx4 v[46:47], v[30:33], off offset:256
	s_waitcnt vmcnt(15)
	s_nop 0
	v_cvt_f32_f16_e32 v30, v134
	v_cvt_f32_f16_sdwa v31, v134 dst_sel:DWORD dst_unused:UNUSED_PAD src0_sel:WORD_1
	v_cvt_f32_f16_e32 v32, v135
	v_cvt_f32_f16_sdwa v33, v135 dst_sel:DWORD dst_unused:UNUSED_PAD src0_sel:WORD_1
	v_pk_fma_f32 v[30:31], v[34:35], v[216:217], v[30:31]
	v_cvt_f32_f16_e32 v34, v136
	v_pk_fma_f32 v[32:33], v[36:37], v[212:213], v[32:33]
	v_cvt_f32_f16_sdwa v35, v136 dst_sel:DWORD dst_unused:UNUSED_PAD src0_sel:WORD_1
	v_cvt_f32_f16_e32 v36, v137
	v_cvt_f32_f16_sdwa v37, v137 dst_sel:DWORD dst_unused:UNUSED_PAD src0_sel:WORD_1
	v_pk_fma_f32 v[36:37], v[28:29], v[204:205], v[36:37]
	v_pk_fma_f32 v[28:29], v[26:27], v[206:207], v[34:35]
	v_med3_f32 v26, v30, s95, v247
	v_med3_f32 v27, v31, s95, v247
	v_cvt_pk_f16_f32 v26, v26, v27
	v_med3_f32 v27, v32, s95, v247
	v_med3_f32 v30, v33, s95, v247
	v_med3_f32 v28, v28, s95, v247
	v_med3_f32 v29, v29, s95, v247
	v_cvt_pk_f16_f32 v27, v27, v30
	v_cvt_pk_f16_f32 v28, v28, v29
	v_med3_f32 v29, v36, s95, v247
	v_med3_f32 v30, v37, s95, v247
	v_cvt_pk_f16_f32 v29, v29, v30
	v_lshl_add_u64 v[30:31], s[26:27], 0, v[220:221]
	v_lshl_add_u64 v[30:31], v[30:31], 0, v[214:215]
	global_store_dwordx4 v[30:31], v[26:29], off
	s_waitcnt vmcnt(15)
	s_nop 0
	v_cvt_f32_f16_e32 v26, v130
	v_cvt_f32_f16_sdwa v27, v130 dst_sel:DWORD dst_unused:UNUSED_PAD src0_sel:WORD_1
	v_cvt_f32_f16_e32 v28, v131
	v_cvt_f32_f16_sdwa v29, v131 dst_sel:DWORD dst_unused:UNUSED_PAD src0_sel:WORD_1
	v_pk_fma_f32 v[22:23], v[22:23], v[210:211], v[26:27]
	v_cvt_f32_f16_e32 v26, v132
	v_pk_fma_f32 v[24:25], v[24:25], v[208:209], v[28:29]
	v_cvt_f32_f16_sdwa v27, v132 dst_sel:DWORD dst_unused:UNUSED_PAD src0_sel:WORD_1
	v_cvt_f32_f16_e32 v28, v133
	v_cvt_f32_f16_sdwa v29, v133 dst_sel:DWORD dst_unused:UNUSED_PAD src0_sel:WORD_1
	v_pk_fma_f32 v[28:29], v[16:17], v[200:201], v[28:29]
	v_pk_fma_f32 v[16:17], v[14:15], v[202:203], v[26:27]
	v_med3_f32 v14, v22, s95, v247
	v_med3_f32 v15, v23, s95, v247
	v_cvt_pk_f16_f32 v14, v14, v15
	v_med3_f32 v15, v24, s95, v247
	v_med3_f32 v22, v25, s95, v247
	v_med3_f32 v16, v16, s95, v247
	v_med3_f32 v17, v17, s95, v247
	v_cvt_pk_f16_f32 v15, v15, v22
	v_cvt_pk_f16_f32 v16, v16, v17
	v_med3_f32 v17, v28, s95, v247
	v_med3_f32 v22, v29, s95, v247
	v_cvt_pk_f16_f32 v17, v17, v22
	global_store_dwordx4 v[30:31], v[14:17], off offset:256
	s_waitcnt vmcnt(15)
	s_nop 0
	v_cvt_f32_f16_e32 v14, v126
	v_cvt_f32_f16_sdwa v15, v126 dst_sel:DWORD dst_unused:UNUSED_PAD src0_sel:WORD_1
	v_cvt_f32_f16_e32 v16, v127
	v_cvt_f32_f16_sdwa v17, v127 dst_sel:DWORD dst_unused:UNUSED_PAD src0_sel:WORD_1
	v_pk_fma_f32 v[14:15], v[18:19], v[216:217], v[14:15]
	v_cvt_f32_f16_e32 v18, v128
	v_pk_fma_f32 v[16:17], v[20:21], v[212:213], v[16:17]
	v_cvt_f32_f16_sdwa v19, v128 dst_sel:DWORD dst_unused:UNUSED_PAD src0_sel:WORD_1
	v_cvt_f32_f16_e32 v20, v129
	v_cvt_f32_f16_sdwa v21, v129 dst_sel:DWORD dst_unused:UNUSED_PAD src0_sel:WORD_1
	v_pk_fma_f32 v[20:21], v[12:13], v[204:205], v[20:21]
	v_pk_fma_f32 v[12:13], v[10:11], v[206:207], v[18:19]
	v_med3_f32 v10, v14, s95, v247
	v_med3_f32 v11, v15, s95, v247
	v_cvt_pk_f16_f32 v10, v10, v11
	v_med3_f32 v11, v16, s95, v247
	v_med3_f32 v14, v17, s95, v247
	v_med3_f32 v12, v12, s95, v247
	v_med3_f32 v13, v13, s95, v247
	v_cvt_pk_f16_f32 v11, v11, v14
	v_cvt_pk_f16_f32 v12, v12, v13
	v_med3_f32 v13, v20, s95, v247
	v_med3_f32 v14, v21, s95, v247
	v_cvt_pk_f16_f32 v13, v13, v14
	v_lshl_add_u64 v[14:15], s[26:27], 0, v[218:219]
	v_lshl_add_u64 v[14:15], v[14:15], 0, v[214:215]
	global_store_dwordx4 v[14:15], v[10:13], off
	s_waitcnt vmcnt(15)
	s_nop 0
	v_cvt_f32_f16_e32 v10, v122
	v_cvt_f32_f16_sdwa v11, v122 dst_sel:DWORD dst_unused:UNUSED_PAD src0_sel:WORD_1
	v_cvt_f32_f16_e32 v12, v123
	v_cvt_f32_f16_sdwa v13, v123 dst_sel:DWORD dst_unused:UNUSED_PAD src0_sel:WORD_1
	v_pk_fma_f32 v[6:7], v[6:7], v[210:211], v[10:11]
	v_cvt_f32_f16_e32 v10, v124
	v_pk_fma_f32 v[8:9], v[8:9], v[208:209], v[12:13]
	v_cvt_f32_f16_sdwa v11, v124 dst_sel:DWORD dst_unused:UNUSED_PAD src0_sel:WORD_1
	v_cvt_f32_f16_e32 v12, v125
	v_cvt_f32_f16_sdwa v13, v125 dst_sel:DWORD dst_unused:UNUSED_PAD src0_sel:WORD_1
	v_pk_fma_f32 v[12:13], v[4:5], v[200:201], v[12:13]
	v_pk_fma_f32 v[4:5], v[2:3], v[202:203], v[10:11]
	v_med3_f32 v2, v6, s95, v247
	v_med3_f32 v3, v7, s95, v247
	v_cvt_pk_f16_f32 v2, v2, v3
	v_med3_f32 v3, v8, s95, v247
	v_med3_f32 v6, v9, s95, v247
	v_med3_f32 v4, v4, s95, v247
	v_med3_f32 v5, v5, s95, v247
	v_cvt_pk_f16_f32 v3, v3, v6
	v_cvt_pk_f16_f32 v4, v4, v5
	v_med3_f32 v5, v12, s95, v247
	v_med3_f32 v6, v13, s95, v247
	v_cvt_pk_f16_f32 v5, v5, v6
	global_store_dwordx4 v[14:15], v[2:5], off offset:256
	s_cbranch_vccnz .LBB0_639
	s_andn2_b64 vcc, exec, s[12:13]
	s_cbranch_vccnz .LBB0_638
	s_barrier
	s_branch .LBB0_638
